# P2 and P11 split-K sample-row units also handed out by atomic ticket (on top of P8 ticket)
# speedup vs baseline: 1.0110x; 1.0051x over previous
.LBB0_341:
	v_cmp_eq_u32_e64 s[100:101], 0, v185
	s_and_saveexec_b64 s[98:99], s[100:101]
	s_cbranch_execz .Lsk2_a
	v_readlane_b32 s100, v251, 6
	v_readlane_b32 s101, v251, 7
	v_mov_b32_e32 v238, 0
	v_mov_b32_e32 v239, 1
	s_nop 3
	global_atomic_add v239, v238, v239, s[100:101] offset:256 sc0
	s_waitcnt vmcnt(0)
	v_mov_b32_e32 v238, 0x26a00
	ds_write_b32 v238, v239
.Lsk2_a:
	s_or_b64 exec, exec, s[98:99]
	s_waitcnt lgkmcnt(0)
	s_barrier
	v_mov_b32_e32 v238, 0x26a00
	ds_read_b32 v238, v238
	s_waitcnt lgkmcnt(0)
	v_readfirstlane_b32 s98, v238
	s_nop 3
	s_and_b32 s100, s98, 1
	s_bfe_u32 s101, s98, 0x20001
	s_add_u32 s74, s50, 0xa9d4000
	s_addc_u32 s75, s51, 0
	s_add_u32 s66, s50, 0x14114000
	s_addc_u32 s67, s51, 0
	s_cmpk_lt_i32 s69, 0x58
	v_writelane_b32 v251, s57, 19
	s_cselect_b64 s[2:3], -1, 0
	v_mov_b32_e32 v12, v185
	v_writelane_b32 v251, s2, 20
	s_and_b32 s96, s69, 1
	s_bfe_u32 s97, s69, 0x20001
	s_movk_i32 s0, 0xb00
	v_readfirstlane_b32 s24, v12
	v_writelane_b32 v251, s3, 21
	s_cmpk_gt_i32 s98, 0x57
	s_cbranch_scc1 .LBB0_355
	v_lshlrev_b32_e32 v2, 4, v12
	v_add_u32_e32 v0, 0x2000, v2
	v_ashrrev_i32_e32 v1, 31, v0
	v_lshrrev_b32_e32 v1, 22, v1
	v_add_u32_e32 v1, v0, v1
	v_ashrrev_i32_e32 v1, 10, v1
	v_mul_i32_i24_e32 v3, 0x400, v1
	v_sub_u32_e32 v0, v0, v3
	v_lshrrev_b32_e32 v3, 4, v0
	v_bitop3_b32 v3, v3, v0, 32 bitop3:0x6c
	v_ashrrev_i32_e32 v0, 31, v3
	v_lshrrev_b32_e32 v0, 26, v0
	v_add_u32_e32 v4, v3, v0
	v_lshlrev_b32_e32 v5, 3, v1
	v_ashrrev_i32_e32 v0, 6, v4
	v_and_b32_e32 v5, 0x7ffffff0, v5
	v_add_u32_e32 v5, v0, v5
	v_lshlrev_b32_e32 v0, 5, v1
	v_and_b32_e32 v0, 32, v0
	v_mad_u64_u32 v[0:1], s[8:9], v5, s0, v[0:1]
	v_and_b32_e32 v1, 0xc0, v4
	v_sub_u32_e32 v1, v3, v1
	v_mov_b32_e32 v3, 1
	v_ashrrev_i16_sdwa v1, v3, sext(v1) dst_sel:DWORD dst_unused:UNUSED_PAD src0_sel:DWORD src1_sel:BYTE_0
	v_bfe_i32 v1, v1, 0, 16
	v_add_lshl_u32 v64, v0, v1, 1
	v_bfe_i32 v0, v12, 27, 1
	v_lshrrev_b32_e32 v0, 22, v0
	v_add_u32_e32 v0, v2, v0
	v_and_b32_e32 v0, 0xfffffc00, v0
	v_sub_u32_e32 v0, v2, v0
	v_lshrrev_b32_e32 v1, 4, v0
	v_bitop3_b32 v2, v1, v0, 32 bitop3:0x6c
	v_ashrrev_i32_e32 v1, 31, v12
	v_lshrrev_b32_e32 v1, 26, v1
	v_ashrrev_i32_e32 v0, 31, v2
	v_add_u32_e32 v1, v12, v1
	v_lshrrev_b32_e32 v0, 26, v0
	v_ashrrev_i32_e32 v1, 6, v1
	v_add_u32_e32 v4, v2, v0
	v_lshlrev_b32_e32 v5, 3, v1
	v_ashrrev_i32_e32 v0, 6, v4
	v_and_b32_e32 v5, 0x7ffffff0, v5
	v_add_u32_e32 v5, v0, v5
	v_lshlrev_b32_e32 v0, 5, v1
	v_and_b32_e32 v0, 32, v0
	v_mad_u64_u32 v[0:1], s[8:9], v5, s0, v[0:1]
	s_ashr_i32 s1, s0, 31
	s_lshl_b32 s8, s98, 5
	s_lshl_b64 s[2:3], s[0:1], 8
	s_lshl_b64 s[4:5], s[0:1], 9
	s_and_b32 s18, s8, 0xffffff00
	s_lshr_b64 s[0:1], s[0:1], 23
	s_ashr_i32 s6, s24, 6
	s_mul_i32 s1, s0, s100
	s_ashr_i32 s19, s18, 31
	s_mul_i32 s0, s0, s101
	s_mul_hi_u32 s11, s4, s101
	s_ashr_i32 s7, s24, 8
	s_lshl_b32 s12, s6, 10
	s_lshl_b64 s[8:9], s[18:19], 1
	s_add_i32 s11, s11, s0
	s_mul_i32 s0, s4, s101
	v_readlane_b32 s14, v251, 17
	v_and_b32_e32 v1, 0xc0, v4
	v_readlane_b32 s15, v251, 18
	s_add_u32 s0, s14, s0
	v_sub_u32_e32 v1, v2, v1
	s_addc_u32 s11, s15, s11
	v_ashrrev_i16_sdwa v1, v3, sext(v1) dst_sel:DWORD dst_unused:UNUSED_PAD src0_sel:DWORD src1_sel:BYTE_0
	s_add_u32 s20, s0, s8
	v_bfe_i32 v1, v1, 0, 16
	s_addc_u32 s21, s11, s9
	s_add_i32 s25, s12, 0
	v_add_lshl_u32 v66, v0, v1, 1
	s_add_i32 m0, s25, 0x10000
	s_mul_i32 s10, s4, s100
	global_load_lds_dwordx4 v66, s[20:21]
	s_add_i32 m0, s25, 0x12000
	s_add_u32 s0, s74, s10
	s_addc_u32 s1, s75, s1
	s_add_u32 s22, s0, s8
	global_load_lds_dwordx4 v64, s[20:21]
	s_addc_u32 s23, s1, s9
	s_mov_b32 m0, s25
	s_add_i32 s26, s25, 0x2000
	global_load_lds_dwordx4 v66, s[22:23]
	s_mov_b32 m0, s26
	s_add_u32 s0, s20, s2
	v_mov_b32_e32 v67, 0
	global_load_lds_dwordx4 v64, s[22:23]
	s_addc_u32 s1, s21, s3
	s_add_i32 m0, s25, 0x14000
	v_mov_b32_e32 v65, v67
	global_load_lds_dwordx4 v66, s[0:1]
	s_add_i32 m0, s25, 0x16000
	v_lshl_add_u64 v[8:9], s[0:1], 0, v[66:67]
	v_lshl_add_u64 v[10:11], s[0:1], 0, v[64:65]
	global_load_lds_dwordx4 v64, s[0:1]
	s_add_u32 s0, s22, s2
	s_addc_u32 s1, s23, s3
	s_add_i32 s27, s25, 0x4000
	s_mov_b32 m0, s27
	s_add_i32 s28, s25, 0x6000
	global_load_lds_dwordx4 v66, s[0:1]
	s_mov_b32 m0, s28
	s_mov_b64 s[80:81], s[52:53]
	global_load_lds_dwordx4 v64, s[0:1]
	v_lshl_add_u64 v[0:1], s[20:21], 0, v[66:67]
	v_lshl_add_u64 v[2:3], s[20:21], 0, v[64:65]
	v_lshl_add_u64 v[4:5], s[22:23], 0, v[66:67]
	v_lshl_add_u64 v[6:7], s[22:23], 0, v[64:65]
	s_cmp_lg_u32 s7, 1
	s_cbranch_scc1 .LBB0_344
	s_barrier
.LBB0_344:
	v_bfe_u32 v14, v12, 4, 2
	v_and_b32_e32 v13, 15, v12
	v_lshlrev_b32_e32 v15, 4, v14
	v_lshlrev_b32_e32 v12, 2, v12
	v_lshl_or_b32 v72, s7, 6, v13
	v_lshl_or_b32 v13, v13, 6, v15
	s_lshl_b32 s0, s7, 13
	v_and_b32_e32 v12, 32, v12
	v_bitop3_b32 v15, v13, s0, v12 bitop3:0xde
	s_lshl_b32 s0, s6, 5
	s_mov_b64 s[6:7], 0x80
	s_add_i32 m0, s25, 0x18000
	v_lshl_add_u64 v[0:1], v[0:1], 0, s[6:7]
	s_waitcnt vmcnt(4)
	s_barrier
	global_load_lds_dwordx4 v[0:1], off
	v_lshl_add_u64 v[0:1], v[2:3], 0, s[6:7]
	s_add_i32 m0, s25, 0x1a000
	s_add_i32 s29, s25, 0x8000
	global_load_lds_dwordx4 v[0:1], off
	v_lshl_add_u64 v[0:1], v[4:5], 0, s[6:7]
	s_mov_b32 m0, s29
	s_add_i32 s30, s25, 0xa000
	global_load_lds_dwordx4 v[0:1], off
	v_lshl_add_u64 v[0:1], v[6:7], 0, s[6:7]
	s_mov_b32 m0, s30
	s_and_b32 s0, s0, 0x60
	global_load_lds_dwordx4 v[0:1], off
	s_add_i32 m0, s25, 0x1c000
	v_lshl_add_u64 v[0:1], v[8:9], 0, s[6:7]
	global_load_lds_dwordx4 v[0:1], off
	v_lshl_add_u64 v[0:1], v[10:11], 0, s[6:7]
	s_add_i32 m0, s25, 0x1e000
	s_lshl_b32 s1, s0, 7
	global_load_lds_dwordx4 v[0:1], off
	v_bitop3_b32 v12, v13, s1, v12 bitop3:0xde
	s_waitcnt vmcnt(6)
	s_add_i32 s39, 0, 0x10000
	s_add_i32 s42, 0, 0x14000
	s_add_i32 s44, 0, 0x18000
	s_add_i32 s46, 0, 0x1c000
	v_lshl_or_b32 v76, v14, 2, s0
	s_add_i32 s0, s58, s98
	v_add_u32_e32 v77, s39, v12
	v_add_u32_e32 v79, s42, v12
	s_add_i32 s39, s39, s12
	s_add_i32 s42, s42, s12
	v_add_u32_e32 v80, s44, v12
	v_add_u32_e32 v81, s46, v12
	s_add_i32 s44, s44, s12
	s_add_i32 s46, s46, s12
	v_or_b32_e32 v73, 16, v72
	v_or_b32_e32 v74, 32, v72
	v_or_b32_e32 v75, 48, v72
	s_lshl_b32 s31, s0, 5
	s_lshl_b32 s33, s58, 5
	v_add_u32_e32 v78, 0, v15
	s_add_i32 s36, s25, 0xc000
	s_add_i32 s37, s25, 0xe000
	s_mov_b64 s[8:9], 0x100
	s_mov_b64 s[10:11], 0x180
	s_add_i32 s41, s39, 0x2000
	s_add_i32 s43, s42, 0x2000
	s_add_i32 s45, s44, 0x2000
	s_add_i32 s47, s46, 0x2000
	s_mov_b32 s48, s98
	s_mov_b32 s51, s101
	s_mov_b32 s52, s100
	s_barrier
	s_branch .LBB0_346

.LBB0_1892:
	v_cmp_eq_u32_e64 s[100:101], 0, v185
	s_and_saveexec_b64 s[98:99], s[100:101]
	s_cbranch_execz .Lsk11_a
	v_readlane_b32 s100, v251, 6
	v_readlane_b32 s101, v251, 7
	v_mov_b32_e32 v238, 0
	v_mov_b32_e32 v239, 1
	s_nop 3
	global_atomic_add v239, v238, v239, s[100:101] offset:768 sc0
	s_waitcnt vmcnt(0)
	v_mov_b32_e32 v238, 0x26a00
	ds_write_b32 v238, v239
.Lsk11_a:
	s_or_b64 exec, exec, s[98:99]
	s_waitcnt lgkmcnt(0)
	s_barrier
	v_mov_b32_e32 v238, 0x26a00
	ds_read_b32 v238, v238
	s_waitcnt lgkmcnt(0)
	v_readfirstlane_b32 s98, v238
	s_nop 3
	s_and_b32 s100, s98, 1
	s_bfe_u32 s101, s98, 0x20001
	v_readlane_b32 s2, v251, 20
	v_readlane_b32 s3, v251, 21
	s_movk_i32 s0, 0xb00
	v_readfirstlane_b32 s26, v185
	s_andn2_b64 vcc, exec, s[2:3]
	s_cmpk_gt_i32 s98, 0x57
	s_cbranch_scc1 .LBB0_1906
	v_lshlrev_b32_e32 v2, 4, v185
	v_add_u32_e32 v0, 0x2000, v2
	v_ashrrev_i32_e32 v1, 31, v0
	v_lshrrev_b32_e32 v1, 22, v1
	v_add_u32_e32 v1, v0, v1
	v_ashrrev_i32_e32 v1, 10, v1
	v_mul_i32_i24_e32 v3, 0x400, v1
	v_sub_u32_e32 v0, v0, v3
	v_lshrrev_b32_e32 v3, 4, v0
	v_bitop3_b32 v3, v3, v0, 32 bitop3:0x6c
	v_ashrrev_i32_e32 v0, 31, v3
	v_lshrrev_b32_e32 v0, 26, v0
	v_add_u32_e32 v4, v3, v0
	v_lshlrev_b32_e32 v5, 3, v1
	v_ashrrev_i32_e32 v0, 6, v4
	v_and_b32_e32 v5, 0x7ffffff0, v5
	v_add_u32_e32 v5, v0, v5
	v_lshlrev_b32_e32 v0, 5, v1
	v_and_b32_e32 v0, 32, v0
	v_mad_u64_u32 v[0:1], s[8:9], v5, s0, v[0:1]
	v_and_b32_e32 v1, 0xc0, v4
	v_sub_u32_e32 v1, v3, v1
	v_mov_b32_e32 v3, 1
	v_ashrrev_i16_sdwa v1, v3, sext(v1) dst_sel:DWORD dst_unused:UNUSED_PAD src0_sel:DWORD src1_sel:BYTE_0
	v_bfe_i32 v1, v1, 0, 16
	v_add_lshl_u32 v64, v0, v1, 1
	v_bfe_i32 v0, v185, 27, 1
	v_lshrrev_b32_e32 v0, 22, v0
	v_add_u32_e32 v0, v2, v0
	v_and_b32_e32 v0, 0xfffffc00, v0
	v_sub_u32_e32 v0, v2, v0
	v_lshrrev_b32_e32 v1, 4, v0
	v_bitop3_b32 v2, v1, v0, 32 bitop3:0x6c
	v_ashrrev_i32_e32 v1, 31, v185
	v_lshrrev_b32_e32 v1, 26, v1
	v_ashrrev_i32_e32 v0, 31, v2
	v_add_u32_e32 v1, v185, v1
	v_lshrrev_b32_e32 v0, 26, v0
	v_ashrrev_i32_e32 v1, 6, v1
	v_add_u32_e32 v4, v2, v0
	v_lshlrev_b32_e32 v5, 3, v1
	v_ashrrev_i32_e32 v0, 6, v4
	v_and_b32_e32 v5, 0x7ffffff0, v5
	v_add_u32_e32 v5, v0, v5
	v_lshlrev_b32_e32 v0, 5, v1
	v_and_b32_e32 v0, 32, v0
	v_mad_u64_u32 v[0:1], s[8:9], v5, s0, v[0:1]
	s_ashr_i32 s1, s0, 31
	s_lshl_b32 s8, s98, 5
	s_lshl_b64 s[2:3], s[0:1], 8
	s_lshl_b64 s[4:5], s[0:1], 9
	s_and_b32 s20, s8, 0xffffff00
	s_lshr_b64 s[0:1], s[0:1], 23
	s_ashr_i32 s10, s26, 6
	s_mul_i32 s1, s0, s100
	s_ashr_i32 s21, s20, 31
	s_mul_i32 s0, s0, s101
	s_mul_hi_u32 s13, s4, s101
	s_ashr_i32 s11, s26, 8
	s_lshl_b32 s14, s10, 10
	s_lshl_b64 s[8:9], s[20:21], 1
	s_add_i32 s13, s13, s0
	s_mul_i32 s0, s4, s101
	v_and_b32_e32 v1, 0xc0, v4
	s_add_u32 s0, s34, s0
	v_sub_u32_e32 v1, v2, v1
	s_addc_u32 s13, s35, s13
	v_ashrrev_i16_sdwa v1, v3, sext(v1) dst_sel:DWORD dst_unused:UNUSED_PAD src0_sel:DWORD src1_sel:BYTE_0
	s_add_u32 s22, s0, s8
	v_bfe_i32 v1, v1, 0, 16
	s_addc_u32 s23, s13, s9
	s_add_i32 s27, s14, 0
	v_add_lshl_u32 v66, v0, v1, 1
	s_add_i32 m0, s27, 0x10000
	s_mul_i32 s12, s4, s100
	global_load_lds_dwordx4 v66, s[22:23]
	s_add_i32 m0, s27, 0x12000
	s_add_u32 s0, s85, s12
	s_addc_u32 s1, s86, s1
	s_add_u32 s24, s0, s8
	global_load_lds_dwordx4 v64, s[22:23]
	s_addc_u32 s25, s1, s9
	s_mov_b32 m0, s27
	s_add_i32 s28, s27, 0x2000
	global_load_lds_dwordx4 v66, s[24:25]
	s_mov_b32 m0, s28
	s_add_u32 s0, s22, s2
	global_load_lds_dwordx4 v64, s[24:25]
	s_addc_u32 s1, s23, s3
	s_add_i32 m0, s27, 0x14000
	v_mov_b32_e32 v67, 0
	global_load_lds_dwordx4 v66, s[0:1]
	s_add_i32 m0, s27, 0x16000
	s_add_u32 s8, s24, s2
	s_addc_u32 s9, s25, s3
	s_add_i32 s29, s27, 0x4000
	global_load_lds_dwordx4 v64, s[0:1]
	s_mov_b32 m0, s29
	s_add_i32 s30, s27, 0x6000
	global_load_lds_dwordx4 v66, s[8:9]
	s_mov_b32 m0, s30
	s_mov_b64 s[66:67], s[54:55]
	global_load_lds_dwordx4 v64, s[8:9]
	v_mov_b32_e32 v65, v67
	s_mov_b64 s[64:65], s[52:53]
	s_mov_b64 s[62:63], s[50:51]
	v_lshl_add_u64 v[10:11], s[22:23], 0, v[66:67]
	v_lshl_add_u64 v[8:9], s[22:23], 0, v[64:65]
	v_lshl_add_u64 v[6:7], s[24:25], 0, v[66:67]
	v_lshl_add_u64 v[4:5], s[24:25], 0, v[64:65]
	v_lshl_add_u64 v[2:3], s[0:1], 0, v[66:67]
	s_cmp_lg_u32 s11, 1
	v_lshl_add_u64 v[0:1], s[0:1], 0, v[64:65]
	s_cbranch_scc1 .LBB0_1895
	s_barrier
.LBB0_1895:
	s_mov_b64 s[8:9], 0x80
	s_add_i32 m0, s27, 0x18000
	v_lshl_add_u64 v[10:11], v[10:11], 0, s[8:9]
	s_waitcnt vmcnt(4)
	s_barrier
	global_load_lds_dwordx4 v[10:11], off
	v_lshl_add_u64 v[8:9], v[8:9], 0, s[8:9]
	s_add_i32 m0, s27, 0x1a000
	s_add_i32 s31, s27, 0x8000
	global_load_lds_dwordx4 v[8:9], off
	v_lshl_add_u64 v[6:7], v[6:7], 0, s[8:9]
	s_mov_b32 m0, s31
	s_add_i32 s33, s27, 0xa000
	global_load_lds_dwordx4 v[6:7], off
	v_lshl_add_u64 v[4:5], v[4:5], 0, s[8:9]
	s_mov_b32 m0, s33
	v_lshl_add_u64 v[2:3], v[2:3], 0, s[8:9]
	global_load_lds_dwordx4 v[4:5], off
	s_add_i32 m0, s27, 0x1c000
	v_lshl_add_u64 v[0:1], v[0:1], 0, s[8:9]
	global_load_lds_dwordx4 v[2:3], off
	s_add_i32 m0, s27, 0x1e000
	s_lshl_b32 s0, s11, 13
	global_load_lds_dwordx4 v[0:1], off
	v_bfe_u32 v1, v185, 4, 2
	v_and_b32_e32 v0, 15, v185
	v_lshlrev_b32_e32 v2, 4, v1
	v_lshl_or_b32 v72, s11, 6, v0
	v_lshl_or_b32 v0, v0, 6, v2
	v_lshlrev_b32_e32 v2, 2, v185
	v_and_b32_e32 v2, 32, v2
	v_bitop3_b32 v3, v0, s0, v2 bitop3:0xde
	s_lshl_b32 s0, s10, 5
	s_and_b32 s0, s0, 0x60
	s_lshl_b32 s1, s0, 7
	v_bitop3_b32 v0, v0, s1, v2 bitop3:0xde
	s_waitcnt vmcnt(6)
	s_add_i32 s40, 0, 0x10000
	s_add_i32 s42, 0, 0x14000
	s_add_i32 s44, 0, 0x18000
	s_add_i32 s46, 0, 0x1c000
	v_lshl_or_b32 v76, v1, 2, s0
	s_add_i32 s0, s94, s98
	v_add_u32_e32 v77, s40, v0
	v_add_u32_e32 v79, s42, v0
	s_add_i32 s40, s40, s14
	s_add_i32 s42, s42, s14
	v_add_u32_e32 v80, s44, v0
	v_add_u32_e32 v81, s46, v0
	s_add_i32 s44, s44, s14
	s_add_i32 s46, s46, s14
	v_or_b32_e32 v73, 16, v72
	v_or_b32_e32 v74, 32, v72
	v_or_b32_e32 v75, 48, v72
	s_lshl_b32 s36, s0, 5
	s_lshl_b32 s37, s94, 5
	v_add_u32_e32 v78, 0, v3
	s_add_i32 s38, s27, 0xc000
	s_add_i32 s39, s27, 0xe000
	s_mov_b64 s[10:11], 0x100
	s_mov_b64 s[12:13], 0x180
	s_add_i32 s41, s40, 0x2000
	s_add_i32 s43, s42, 0x2000
	s_add_i32 s45, s44, 0x2000
	s_add_i32 s47, s46, 0x2000
	s_barrier
	s_branch .LBB0_1897
.LBB0_1896:
	ds_read_b128 v[4:7], v77
	ds_read_b128 v[8:11], v77 offset:1024
	ds_read_b128 v[12:15], v77 offset:2048
	ds_read_b128 v[16:19], v77 offset:3072
	s_add_u32 s50, s24, s2
	s_addc_u32 s51, s25, s3
	v_lshl_add_u64 v[0:1], s[50:51], 0, v[66:67]
	s_mov_b32 m0, s38
	v_lshl_add_u64 v[2:3], v[0:1], 0, s[8:9]
	ds_read_b128 v[20:23], v78
	ds_read_b128 v[24:27], v78 offset:1024
	ds_read_b128 v[28:31], v78 offset:2048
	ds_read_b128 v[32:35], v78 offset:3072
	ds_read_b128 v[36:39], v78 offset:4096
	ds_read_b128 v[40:43], v78 offset:5120
	ds_read_b128 v[44:47], v78 offset:6144
	ds_read_b128 v[48:51], v78 offset:7168
	global_load_lds_dwordx4 v[2:3], off
	v_lshl_add_u64 v[2:3], s[50:51], 0, v[64:65]
	v_lshl_add_u64 v[52:53], v[2:3], 0, s[8:9]
	s_mov_b32 m0, s39
	s_nop 0
	global_load_lds_dwordx4 v[52:53], off
	s_waitcnt lgkmcnt(8)
	s_barrier
	s_waitcnt lgkmcnt(0)
	s_waitcnt lgkmcnt(0)
	v_mfma_f32_16x16x32_bf16 v[52:55], v[4:7], v[20:23], 0
	v_mfma_f32_16x16x32_bf16 v[56:59], v[12:15], v[20:23], 0
	v_mfma_f32_16x16x32_bf16 v[60:63], v[4:7], v[28:31], 0
	v_mfma_f32_16x16x32_bf16 v[68:71], v[12:15], v[28:31], 0
	v_mfma_f32_16x16x32_bf16 v[82:85], v[4:7], v[36:39], 0
	v_mfma_f32_16x16x32_bf16 v[86:89], v[12:15], v[36:39], 0
	v_mfma_f32_16x16x32_bf16 v[90:93], v[4:7], v[44:47], 0
	v_mfma_f32_16x16x32_bf16 v[94:97], v[12:15], v[44:47], 0
	v_mfma_f32_16x16x32_bf16 v[52:55], v[8:11], v[24:27], v[52:55]
	v_mfma_f32_16x16x32_bf16 v[56:59], v[16:19], v[24:27], v[56:59]
	v_mfma_f32_16x16x32_bf16 v[60:63], v[8:11], v[32:35], v[60:63]
	v_mfma_f32_16x16x32_bf16 v[68:71], v[16:19], v[32:35], v[68:71]
	v_mfma_f32_16x16x32_bf16 v[82:85], v[8:11], v[40:43], v[82:85]
	v_mfma_f32_16x16x32_bf16 v[86:89], v[16:19], v[40:43], v[86:89]
	v_mfma_f32_16x16x32_bf16 v[90:93], v[8:11], v[48:51], v[90:93]
	v_mfma_f32_16x16x32_bf16 v[94:97], v[16:19], v[48:51], v[94:97]
	s_barrier
	v_lshl_add_u64 v[182:183], s[22:23], 0, v[66:67]
	s_mov_b32 m0, s40
	v_lshl_add_u64 v[114:115], v[182:183], 0, s[10:11]
	v_lshl_add_u64 v[216:217], s[22:23], 0, v[64:65]
	ds_read_b128 v[98:101], v79
	ds_read_b128 v[102:105], v79 offset:1024
	ds_read_b128 v[106:109], v79 offset:2048
	ds_read_b128 v[110:113], v79 offset:3072
	global_load_lds_dwordx4 v[114:115], off
	v_lshl_add_u64 v[114:115], v[216:217], 0, s[10:11]
	s_mov_b32 m0, s41
	s_nop 0
	global_load_lds_dwordx4 v[114:115], off
	s_barrier
	s_waitcnt lgkmcnt(0)
	s_waitcnt lgkmcnt(0)
	v_mfma_f32_16x16x32_bf16 v[114:117], v[98:101], v[20:23], 0
	v_mfma_f32_16x16x32_bf16 v[20:23], v[106:109], v[20:23], 0
	v_mfma_f32_16x16x32_bf16 v[114:117], v[102:105], v[24:27], v[114:117]
	v_mfma_f32_16x16x32_bf16 v[20:23], v[110:113], v[24:27], v[20:23]
	v_mfma_f32_16x16x32_bf16 v[24:27], v[98:101], v[28:31], 0
	v_mfma_f32_16x16x32_bf16 v[28:31], v[106:109], v[28:31], 0
	v_mfma_f32_16x16x32_bf16 v[24:27], v[102:105], v[32:35], v[24:27]
	v_mfma_f32_16x16x32_bf16 v[28:31], v[110:113], v[32:35], v[28:31]
	v_mfma_f32_16x16x32_bf16 v[32:35], v[98:101], v[36:39], 0
	v_mfma_f32_16x16x32_bf16 v[36:39], v[106:109], v[36:39], 0
	v_mfma_f32_16x16x32_bf16 v[32:35], v[102:105], v[40:43], v[32:35]
	v_mfma_f32_16x16x32_bf16 v[36:39], v[110:113], v[40:43], v[36:39]
	v_mfma_f32_16x16x32_bf16 v[40:43], v[98:101], v[44:47], 0
	v_mfma_f32_16x16x32_bf16 v[44:47], v[106:109], v[44:47], 0
	v_mfma_f32_16x16x32_bf16 v[40:43], v[102:105], v[48:51], v[40:43]
	v_mfma_f32_16x16x32_bf16 v[44:47], v[110:113], v[48:51], v[44:47]
	v_lshl_add_u64 v[218:219], s[24:25], 0, v[66:67]
	s_mov_b32 m0, s27
	v_lshl_add_u64 v[146:147], v[218:219], 0, s[10:11]
	v_lshl_add_u64 v[220:221], s[24:25], 0, v[64:65]
	s_barrier
	ds_read_b128 v[48:51], v78 offset:16384
	ds_read_b128 v[118:121], v78 offset:17408
	ds_read_b128 v[122:125], v78 offset:18432
	ds_read_b128 v[126:129], v78 offset:19456
	ds_read_b128 v[130:133], v78 offset:20480
	ds_read_b128 v[134:137], v78 offset:21504
	ds_read_b128 v[138:141], v78 offset:22528
	ds_read_b128 v[142:145], v78 offset:23552
	global_load_lds_dwordx4 v[146:147], off
	v_lshl_add_u64 v[146:147], v[220:221], 0, s[10:11]
	s_mov_b32 m0, s28
	s_nop 0
	global_load_lds_dwordx4 v[146:147], off
	s_barrier
	s_waitcnt lgkmcnt(0)
	s_waitcnt lgkmcnt(0)
	v_mfma_f32_16x16x32_bf16 v[146:149], v[4:7], v[48:51], 0
	v_mfma_f32_16x16x32_bf16 v[154:157], v[4:7], v[122:125], 0
	v_mfma_f32_16x16x32_bf16 v[162:165], v[4:7], v[130:133], 0
	v_mfma_f32_16x16x32_bf16 v[4:7], v[4:7], v[138:141], 0
	v_mfma_f32_16x16x32_bf16 v[146:149], v[8:11], v[118:121], v[146:149]
	v_mfma_f32_16x16x32_bf16 v[150:153], v[12:15], v[48:51], 0
	v_mfma_f32_16x16x32_bf16 v[154:157], v[8:11], v[126:129], v[154:157]
	v_mfma_f32_16x16x32_bf16 v[158:161], v[12:15], v[122:125], 0
	v_mfma_f32_16x16x32_bf16 v[162:165], v[8:11], v[134:137], v[162:165]
	v_mfma_f32_16x16x32_bf16 v[166:169], v[12:15], v[130:133], 0
	v_mfma_f32_16x16x32_bf16 v[4:7], v[8:11], v[142:145], v[4:7]
	v_mfma_f32_16x16x32_bf16 v[8:11], v[12:15], v[138:141], 0
	v_mfma_f32_16x16x32_bf16 v[150:153], v[16:19], v[118:121], v[150:153]
	v_mfma_f32_16x16x32_bf16 v[158:161], v[16:19], v[126:129], v[158:161]
	v_mfma_f32_16x16x32_bf16 v[166:169], v[16:19], v[134:137], v[166:169]
	v_mfma_f32_16x16x32_bf16 v[8:11], v[16:19], v[142:145], v[8:11]
	s_barrier
	s_add_u32 s22, s22, s2
	s_addc_u32 s23, s23, s3
	v_lshl_add_u64 v[222:223], s[22:23], 0, v[66:67]
	s_mov_b32 m0, s42
	v_lshl_add_u64 v[12:13], v[222:223], 0, s[10:11]
	v_lshl_add_u64 v[224:225], s[22:23], 0, v[64:65]
	global_load_lds_dwordx4 v[12:13], off
	v_lshl_add_u64 v[12:13], v[224:225], 0, s[10:11]
	s_mov_b32 m0, s43
	s_nop 0
	global_load_lds_dwordx4 v[12:13], off
	s_waitcnt vmcnt(6)
	s_barrier
	v_mfma_f32_16x16x32_bf16 v[12:15], v[98:101], v[48:51], 0
	v_mfma_f32_16x16x32_bf16 v[16:19], v[106:109], v[48:51], 0
	v_mfma_f32_16x16x32_bf16 v[12:15], v[102:105], v[118:121], v[12:15]
	v_mfma_f32_16x16x32_bf16 v[16:19], v[110:113], v[118:121], v[16:19]
	v_mfma_f32_16x16x32_bf16 v[48:51], v[98:101], v[122:125], 0
	v_mfma_f32_16x16x32_bf16 v[118:121], v[106:109], v[122:125], 0
	v_mfma_f32_16x16x32_bf16 v[122:125], v[98:101], v[130:133], 0
	v_mfma_f32_16x16x32_bf16 v[98:101], v[98:101], v[138:141], 0
	v_mfma_f32_16x16x32_bf16 v[48:51], v[102:105], v[126:129], v[48:51]
	v_mfma_f32_16x16x32_bf16 v[118:121], v[110:113], v[126:129], v[118:121]
	v_mfma_f32_16x16x32_bf16 v[122:125], v[102:105], v[134:137], v[122:125]
	v_mfma_f32_16x16x32_bf16 v[126:129], v[106:109], v[130:133], 0
	v_mfma_f32_16x16x32_bf16 v[98:101], v[102:105], v[142:145], v[98:101]
	v_mfma_f32_16x16x32_bf16 v[102:105], v[106:109], v[138:141], 0
	v_mfma_f32_16x16x32_bf16 v[126:129], v[110:113], v[134:137], v[126:129]
	v_mfma_f32_16x16x32_bf16 v[102:105], v[110:113], v[142:145], v[102:105]
	s_barrier
	ds_read_b128 v[106:109], v80
	ds_read_b128 v[110:113], v80 offset:1024
	ds_read_b128 v[130:133], v80 offset:2048
	ds_read_b128 v[134:137], v80 offset:3072
	s_mov_b32 m0, s29
	v_lshl_add_u64 v[200:201], v[0:1], 0, s[10:11]
	ds_read_b128 v[138:141], v78 offset:32768
	ds_read_b128 v[142:145], v78 offset:33792
	ds_read_b128 v[170:173], v78 offset:34816
	ds_read_b128 v[174:177], v78 offset:35840
	ds_read_b128 v[178:181], v78 offset:36864
	ds_read_b128 v[186:189], v78 offset:37888
	ds_read_b128 v[190:193], v78 offset:38912
	ds_read_b128 v[194:197], v78 offset:39936
	global_load_lds_dwordx4 v[200:201], off
	v_lshl_add_u64 v[200:201], v[2:3], 0, s[10:11]
	s_mov_b32 m0, s30
	s_nop 0
	global_load_lds_dwordx4 v[200:201], off
	s_waitcnt lgkmcnt(8)
	s_barrier
	s_waitcnt lgkmcnt(0)
	s_waitcnt lgkmcnt(0)
	v_mfma_f32_16x16x32_bf16 v[52:55], v[106:109], v[138:141], v[52:55]
	v_mfma_f32_16x16x32_bf16 v[56:59], v[130:133], v[138:141], v[56:59]
	v_mfma_f32_16x16x32_bf16 v[60:63], v[106:109], v[170:173], v[60:63]
	v_mfma_f32_16x16x32_bf16 v[68:71], v[130:133], v[170:173], v[68:71]
	v_mfma_f32_16x16x32_bf16 v[82:85], v[106:109], v[178:181], v[82:85]
	v_mfma_f32_16x16x32_bf16 v[86:89], v[130:133], v[178:181], v[86:89]
	v_mfma_f32_16x16x32_bf16 v[90:93], v[106:109], v[190:193], v[90:93]
	v_mfma_f32_16x16x32_bf16 v[94:97], v[130:133], v[190:193], v[94:97]
	v_mfma_f32_16x16x32_bf16 v[52:55], v[110:113], v[142:145], v[52:55]
	v_mfma_f32_16x16x32_bf16 v[56:59], v[134:137], v[142:145], v[56:59]
	v_mfma_f32_16x16x32_bf16 v[60:63], v[110:113], v[174:177], v[60:63]
	v_mfma_f32_16x16x32_bf16 v[68:71], v[134:137], v[174:177], v[68:71]
	v_mfma_f32_16x16x32_bf16 v[82:85], v[110:113], v[186:189], v[82:85]
	v_mfma_f32_16x16x32_bf16 v[86:89], v[134:137], v[186:189], v[86:89]
	v_mfma_f32_16x16x32_bf16 v[90:93], v[110:113], v[194:197], v[90:93]
	v_mfma_f32_16x16x32_bf16 v[94:97], v[134:137], v[194:197], v[94:97]
	s_barrier
	s_mov_b32 m0, s44
	v_lshl_add_u64 v[182:183], v[182:183], 0, s[12:13]
	ds_read_b128 v[200:203], v81
	ds_read_b128 v[204:207], v81 offset:1024
	ds_read_b128 v[208:211], v81 offset:2048
	ds_read_b128 v[212:215], v81 offset:3072
	global_load_lds_dwordx4 v[182:183], off
	v_lshl_add_u64 v[182:183], v[216:217], 0, s[12:13]
	s_mov_b32 m0, s45
	s_nop 0
	global_load_lds_dwordx4 v[182:183], off
	s_barrier
	s_waitcnt lgkmcnt(0)
	s_waitcnt lgkmcnt(0)
	v_mfma_f32_16x16x32_bf16 v[114:117], v[200:203], v[138:141], v[114:117]
	v_mfma_f32_16x16x32_bf16 v[20:23], v[208:211], v[138:141], v[20:23]
	v_mfma_f32_16x16x32_bf16 v[24:27], v[200:203], v[170:173], v[24:27]
	v_mfma_f32_16x16x32_bf16 v[28:31], v[208:211], v[170:173], v[28:31]
	v_mfma_f32_16x16x32_bf16 v[32:35], v[200:203], v[178:181], v[32:35]
	v_mfma_f32_16x16x32_bf16 v[36:39], v[208:211], v[178:181], v[36:39]
	v_mfma_f32_16x16x32_bf16 v[40:43], v[200:203], v[190:193], v[40:43]
	v_mfma_f32_16x16x32_bf16 v[44:47], v[208:211], v[190:193], v[44:47]
	v_mfma_f32_16x16x32_bf16 v[114:117], v[204:207], v[142:145], v[114:117]
	v_mfma_f32_16x16x32_bf16 v[20:23], v[212:215], v[142:145], v[20:23]
	v_mfma_f32_16x16x32_bf16 v[24:27], v[204:207], v[174:177], v[24:27]
	v_mfma_f32_16x16x32_bf16 v[28:31], v[212:215], v[174:177], v[28:31]
	v_mfma_f32_16x16x32_bf16 v[32:35], v[204:207], v[186:189], v[32:35]
	v_mfma_f32_16x16x32_bf16 v[36:39], v[212:215], v[186:189], v[36:39]
	v_mfma_f32_16x16x32_bf16 v[40:43], v[204:207], v[194:197], v[40:43]
	v_mfma_f32_16x16x32_bf16 v[44:47], v[212:215], v[194:197], v[44:47]
	s_mov_b32 m0, s31
	v_lshl_add_u64 v[182:183], v[218:219], 0, s[12:13]
	s_barrier
	ds_read_b128 v[138:141], v78 offset:49152
	ds_read_b128 v[142:145], v78 offset:50176
	ds_read_b128 v[170:173], v78 offset:51200
	ds_read_b128 v[174:177], v78 offset:52224
	ds_read_b128 v[178:181], v78 offset:53248
	ds_read_b128 v[186:189], v78 offset:54272
	ds_read_b128 v[190:193], v78 offset:55296
	ds_read_b128 v[194:197], v78 offset:56320
	global_load_lds_dwordx4 v[182:183], off
	v_lshl_add_u64 v[182:183], v[220:221], 0, s[12:13]
	s_mov_b32 m0, s33
	s_nop 0
	global_load_lds_dwordx4 v[182:183], off
	s_barrier
	s_waitcnt lgkmcnt(0)
	s_waitcnt lgkmcnt(0)
	v_mfma_f32_16x16x32_bf16 v[146:149], v[106:109], v[138:141], v[146:149]
	v_mfma_f32_16x16x32_bf16 v[150:153], v[130:133], v[138:141], v[150:153]
	v_mfma_f32_16x16x32_bf16 v[154:157], v[106:109], v[170:173], v[154:157]
	v_mfma_f32_16x16x32_bf16 v[158:161], v[130:133], v[170:173], v[158:161]
	v_mfma_f32_16x16x32_bf16 v[162:165], v[106:109], v[178:181], v[162:165]
	v_mfma_f32_16x16x32_bf16 v[166:169], v[130:133], v[178:181], v[166:169]
	v_mfma_f32_16x16x32_bf16 v[4:7], v[106:109], v[190:193], v[4:7]
	v_mfma_f32_16x16x32_bf16 v[8:11], v[130:133], v[190:193], v[8:11]
	v_mfma_f32_16x16x32_bf16 v[146:149], v[110:113], v[142:145], v[146:149]
	v_mfma_f32_16x16x32_bf16 v[150:153], v[134:137], v[142:145], v[150:153]
	v_mfma_f32_16x16x32_bf16 v[154:157], v[110:113], v[174:177], v[154:157]
	v_mfma_f32_16x16x32_bf16 v[158:161], v[134:137], v[174:177], v[158:161]
	v_mfma_f32_16x16x32_bf16 v[162:165], v[110:113], v[186:189], v[162:165]
	v_mfma_f32_16x16x32_bf16 v[166:169], v[134:137], v[186:189], v[166:169]
	v_mfma_f32_16x16x32_bf16 v[4:7], v[110:113], v[194:197], v[4:7]
	v_mfma_f32_16x16x32_bf16 v[8:11], v[134:137], v[194:197], v[8:11]
	s_barrier
	s_mov_b32 m0, s46
	v_lshl_add_u64 v[106:107], v[222:223], 0, s[12:13]
	global_load_lds_dwordx4 v[106:107], off
	v_lshl_add_u64 v[106:107], v[224:225], 0, s[12:13]
	s_mov_b32 m0, s47
	s_nop 0
	global_load_lds_dwordx4 v[106:107], off
	s_waitcnt vmcnt(6)
	s_barrier
	v_mfma_f32_16x16x32_bf16 v[12:15], v[200:203], v[138:141], v[12:15]
	v_mfma_f32_16x16x32_bf16 v[16:19], v[208:211], v[138:141], v[16:19]
	v_mfma_f32_16x16x32_bf16 v[48:51], v[200:203], v[170:173], v[48:51]
	v_mfma_f32_16x16x32_bf16 v[106:109], v[208:211], v[170:173], v[118:121]
	v_mfma_f32_16x16x32_bf16 v[110:113], v[200:203], v[178:181], v[122:125]
	v_mfma_f32_16x16x32_bf16 v[118:121], v[208:211], v[178:181], v[126:129]
	v_mfma_f32_16x16x32_bf16 v[98:101], v[200:203], v[190:193], v[98:101]
	v_mfma_f32_16x16x32_bf16 v[102:105], v[208:211], v[190:193], v[102:105]
	v_mfma_f32_16x16x32_bf16 v[12:15], v[204:207], v[142:145], v[12:15]
	v_mfma_f32_16x16x32_bf16 v[16:19], v[212:215], v[142:145], v[16:19]
	v_mfma_f32_16x16x32_bf16 v[48:51], v[204:207], v[174:177], v[48:51]
	v_mfma_f32_16x16x32_bf16 v[106:109], v[212:215], v[174:177], v[106:109]
	v_mfma_f32_16x16x32_bf16 v[110:113], v[204:207], v[186:189], v[110:113]
	v_mfma_f32_16x16x32_bf16 v[118:121], v[212:215], v[186:189], v[118:121]
	v_mfma_f32_16x16x32_bf16 v[98:101], v[204:207], v[194:197], v[98:101]
	v_mfma_f32_16x16x32_bf16 v[102:105], v[212:215], v[194:197], v[102:105]
	s_barrier
	ds_read_b128 v[122:125], v77
	ds_read_b128 v[126:129], v77 offset:1024
	ds_read_b128 v[130:133], v77 offset:2048
	ds_read_b128 v[134:137], v77 offset:3072
	s_mov_b32 m0, s38
	v_lshl_add_u64 v[0:1], v[0:1], 0, s[12:13]
	ds_read_b128 v[138:141], v78
	ds_read_b128 v[142:145], v78 offset:1024
	ds_read_b128 v[170:173], v78 offset:2048
	ds_read_b128 v[174:177], v78 offset:3072
	ds_read_b128 v[178:181], v78 offset:4096
	ds_read_b128 v[186:189], v78 offset:5120
	ds_read_b128 v[190:193], v78 offset:6144
	ds_read_b128 v[194:197], v78 offset:7168
	global_load_lds_dwordx4 v[0:1], off
	v_lshl_add_u64 v[0:1], v[2:3], 0, s[12:13]
	s_mov_b32 m0, s39
	s_nop 0
	global_load_lds_dwordx4 v[0:1], off
	s_waitcnt lgkmcnt(8)
	s_barrier
	s_waitcnt lgkmcnt(0)
	s_waitcnt lgkmcnt(0)
	v_mfma_f32_16x16x32_bf16 v[0:3], v[122:125], v[138:141], v[52:55]
	v_mfma_f32_16x16x32_bf16 v[52:55], v[130:133], v[138:141], v[56:59]
	v_mfma_f32_16x16x32_bf16 v[56:59], v[122:125], v[170:173], v[60:63]
	v_mfma_f32_16x16x32_bf16 v[60:63], v[130:133], v[170:173], v[68:71]
	v_mfma_f32_16x16x32_bf16 v[68:71], v[122:125], v[178:181], v[82:85]
	v_mfma_f32_16x16x32_bf16 v[82:85], v[130:133], v[178:181], v[86:89]
	v_mfma_f32_16x16x32_bf16 v[86:89], v[122:125], v[190:193], v[90:93]
	v_mfma_f32_16x16x32_bf16 v[90:93], v[130:133], v[190:193], v[94:97]
	v_mfma_f32_16x16x32_bf16 v[0:3], v[126:129], v[142:145], v[0:3]
	v_mfma_f32_16x16x32_bf16 v[52:55], v[134:137], v[142:145], v[52:55]
	v_mfma_f32_16x16x32_bf16 v[56:59], v[126:129], v[174:177], v[56:59]
	v_mfma_f32_16x16x32_bf16 v[60:63], v[134:137], v[174:177], v[60:63]
	v_mfma_f32_16x16x32_bf16 v[68:71], v[126:129], v[186:189], v[68:71]
	v_mfma_f32_16x16x32_bf16 v[82:85], v[134:137], v[186:189], v[82:85]
	v_mfma_f32_16x16x32_bf16 v[86:89], v[126:129], v[194:197], v[86:89]
	v_mfma_f32_16x16x32_bf16 v[90:93], v[134:137], v[194:197], v[90:93]
	s_barrier
	s_mov_b32 m0, s40
	v_lshl_add_u64 v[182:183], s[0:1], 0, v[66:67]
	ds_read_b128 v[94:97], v79
	ds_read_b128 v[200:203], v79 offset:1024
	ds_read_b128 v[204:207], v79 offset:2048
	ds_read_b128 v[208:211], v79 offset:3072
	global_load_lds_dwordx4 v[182:183], off
	v_lshl_add_u64 v[224:225], s[0:1], 0, v[64:65]
	s_mov_b32 m0, s41
	s_nop 0
	global_load_lds_dwordx4 v[224:225], off
	s_barrier
	s_waitcnt lgkmcnt(0)
	s_waitcnt lgkmcnt(0)
	v_mfma_f32_16x16x32_bf16 v[114:117], v[94:97], v[138:141], v[114:117]
	v_mfma_f32_16x16x32_bf16 v[20:23], v[204:207], v[138:141], v[20:23]
	v_mfma_f32_16x16x32_bf16 v[24:27], v[94:97], v[170:173], v[24:27]
	v_mfma_f32_16x16x32_bf16 v[28:31], v[204:207], v[170:173], v[28:31]
	v_mfma_f32_16x16x32_bf16 v[32:35], v[94:97], v[178:181], v[32:35]
	v_mfma_f32_16x16x32_bf16 v[36:39], v[204:207], v[178:181], v[36:39]
	v_mfma_f32_16x16x32_bf16 v[40:43], v[94:97], v[190:193], v[40:43]
	v_mfma_f32_16x16x32_bf16 v[44:47], v[204:207], v[190:193], v[44:47]
	v_mfma_f32_16x16x32_bf16 v[114:117], v[200:203], v[142:145], v[114:117]
	v_mfma_f32_16x16x32_bf16 v[20:23], v[208:211], v[142:145], v[20:23]
	v_mfma_f32_16x16x32_bf16 v[24:27], v[200:203], v[174:177], v[24:27]
	v_mfma_f32_16x16x32_bf16 v[28:31], v[208:211], v[174:177], v[28:31]
	v_mfma_f32_16x16x32_bf16 v[32:35], v[200:203], v[186:189], v[32:35]
	v_mfma_f32_16x16x32_bf16 v[36:39], v[208:211], v[186:189], v[36:39]
	v_mfma_f32_16x16x32_bf16 v[40:43], v[200:203], v[194:197], v[40:43]
	v_mfma_f32_16x16x32_bf16 v[44:47], v[208:211], v[194:197], v[44:47]
	s_mov_b32 m0, s27
	v_lshl_add_u64 v[240:241], s[18:19], 0, v[66:67]
	s_barrier
	ds_read_b128 v[138:141], v78 offset:16384
	ds_read_b128 v[142:145], v78 offset:17408
	ds_read_b128 v[170:173], v78 offset:18432
	ds_read_b128 v[174:177], v78 offset:19456
	ds_read_b128 v[178:181], v78 offset:20480
	ds_read_b128 v[186:189], v78 offset:21504
	ds_read_b128 v[190:193], v78 offset:22528
	ds_read_b128 v[194:197], v78 offset:23552
	global_load_lds_dwordx4 v[240:241], off
	v_lshl_add_u64 v[242:243], s[18:19], 0, v[64:65]
	s_mov_b32 m0, s28
	s_nop 0
	global_load_lds_dwordx4 v[242:243], off
	s_barrier
	s_waitcnt lgkmcnt(0)
	s_waitcnt lgkmcnt(0)
	v_mfma_f32_16x16x32_bf16 v[146:149], v[122:125], v[138:141], v[146:149]
	v_mfma_f32_16x16x32_bf16 v[150:153], v[130:133], v[138:141], v[150:153]
	v_mfma_f32_16x16x32_bf16 v[154:157], v[122:125], v[170:173], v[154:157]
	v_mfma_f32_16x16x32_bf16 v[158:161], v[130:133], v[170:173], v[158:161]
	v_mfma_f32_16x16x32_bf16 v[162:165], v[122:125], v[178:181], v[162:165]
	v_mfma_f32_16x16x32_bf16 v[166:169], v[130:133], v[178:181], v[166:169]
	v_mfma_f32_16x16x32_bf16 v[4:7], v[122:125], v[190:193], v[4:7]
	v_mfma_f32_16x16x32_bf16 v[8:11], v[130:133], v[190:193], v[8:11]
	v_mfma_f32_16x16x32_bf16 v[146:149], v[126:129], v[142:145], v[146:149]
	v_mfma_f32_16x16x32_bf16 v[150:153], v[134:137], v[142:145], v[150:153]
	v_mfma_f32_16x16x32_bf16 v[154:157], v[126:129], v[174:177], v[154:157]
	v_mfma_f32_16x16x32_bf16 v[158:161], v[134:137], v[174:177], v[158:161]
	v_mfma_f32_16x16x32_bf16 v[162:165], v[126:129], v[186:189], v[162:165]
	v_mfma_f32_16x16x32_bf16 v[166:169], v[134:137], v[186:189], v[166:169]
	v_mfma_f32_16x16x32_bf16 v[4:7], v[126:129], v[194:197], v[4:7]
	v_mfma_f32_16x16x32_bf16 v[8:11], v[134:137], v[194:197], v[8:11]
	s_barrier
	s_add_u32 s22, s0, s2
	s_addc_u32 s23, s1, s3
	s_mov_b32 m0, s42
	v_lshl_add_u64 v[244:245], s[22:23], 0, v[66:67]
	global_load_lds_dwordx4 v[244:245], off
	v_lshl_add_u64 v[246:247], s[22:23], 0, v[64:65]
	s_mov_b32 m0, s43
	s_nop 0
	global_load_lds_dwordx4 v[246:247], off
	s_waitcnt vmcnt(6)
	s_barrier
	v_mfma_f32_16x16x32_bf16 v[16:19], v[204:207], v[138:141], v[16:19]
	v_mfma_f32_16x16x32_bf16 v[122:125], v[208:211], v[142:145], v[16:19]
	v_mfma_f32_16x16x32_bf16 v[16:19], v[94:97], v[170:173], v[48:51]
	v_mfma_f32_16x16x32_bf16 v[126:129], v[200:203], v[174:177], v[16:19]
	v_mfma_f32_16x16x32_bf16 v[16:19], v[204:207], v[170:173], v[106:109]
	v_mfma_f32_16x16x32_bf16 v[106:109], v[208:211], v[174:177], v[16:19]
	v_mfma_f32_16x16x32_bf16 v[16:19], v[94:97], v[178:181], v[110:113]
	v_mfma_f32_16x16x32_bf16 v[110:113], v[200:203], v[186:189], v[16:19]
	v_mfma_f32_16x16x32_bf16 v[16:19], v[204:207], v[178:181], v[118:121]
	v_mfma_f32_16x16x32_bf16 v[118:121], v[208:211], v[186:189], v[16:19]
	v_mfma_f32_16x16x32_bf16 v[16:19], v[94:97], v[190:193], v[98:101]
	v_mfma_f32_16x16x32_bf16 v[12:15], v[94:97], v[138:141], v[12:15]
	v_mfma_f32_16x16x32_bf16 v[94:97], v[200:203], v[194:197], v[16:19]
	v_mfma_f32_16x16x32_bf16 v[16:19], v[204:207], v[190:193], v[102:105]
	v_mfma_f32_16x16x32_bf16 v[12:15], v[200:203], v[142:145], v[12:15]
	v_mfma_f32_16x16x32_bf16 v[98:101], v[208:211], v[194:197], v[16:19]
	s_barrier
	ds_read_b128 v[102:105], v80
	ds_read_b128 v[130:133], v80 offset:1024
	ds_read_b128 v[134:137], v80 offset:2048
	ds_read_b128 v[138:141], v80 offset:3072
	s_add_u32 s22, s18, s2
	s_addc_u32 s23, s19, s3
	s_mov_b32 m0, s29
	v_lshl_add_u64 v[48:49], s[22:23], 0, v[66:67]
	ds_read_b128 v[16:19], v78 offset:32768
	ds_read_b128 v[142:145], v78 offset:33792
	ds_read_b128 v[170:173], v78 offset:34816
	ds_read_b128 v[174:177], v78 offset:35840
	ds_read_b128 v[178:181], v78 offset:36864
	ds_read_b128 v[186:189], v78 offset:37888
	ds_read_b128 v[190:193], v78 offset:38912
	ds_read_b128 v[194:197], v78 offset:39936
	global_load_lds_dwordx4 v[48:49], off
	v_lshl_add_u64 v[48:49], s[22:23], 0, v[64:65]
	s_mov_b32 m0, s30
	s_nop 0
	global_load_lds_dwordx4 v[48:49], off
	s_waitcnt lgkmcnt(8)
	s_barrier
	s_waitcnt lgkmcnt(0)
	s_waitcnt lgkmcnt(0)
	v_mfma_f32_16x16x32_bf16 v[0:3], v[102:105], v[16:19], v[0:3]
	v_mfma_f32_16x16x32_bf16 v[200:203], v[130:133], v[142:145], v[0:3]
	v_mfma_f32_16x16x32_bf16 v[0:3], v[134:137], v[16:19], v[52:55]
	v_mfma_f32_16x16x32_bf16 v[204:207], v[138:141], v[142:145], v[0:3]
	v_mfma_f32_16x16x32_bf16 v[0:3], v[102:105], v[170:173], v[56:59]
	v_mfma_f32_16x16x32_bf16 v[208:211], v[130:133], v[174:177], v[0:3]
	v_mfma_f32_16x16x32_bf16 v[0:3], v[134:137], v[170:173], v[60:63]
	v_mfma_f32_16x16x32_bf16 v[212:215], v[138:141], v[174:177], v[0:3]
	v_mfma_f32_16x16x32_bf16 v[0:3], v[102:105], v[178:181], v[68:71]
	v_mfma_f32_16x16x32_bf16 v[216:219], v[130:133], v[186:189], v[0:3]
	v_mfma_f32_16x16x32_bf16 v[0:3], v[134:137], v[178:181], v[82:85]
	v_mfma_f32_16x16x32_bf16 v[82:85], v[138:141], v[186:189], v[0:3]
	v_mfma_f32_16x16x32_bf16 v[0:3], v[102:105], v[190:193], v[86:89]
	v_mfma_f32_16x16x32_bf16 v[52:55], v[130:133], v[194:197], v[0:3]
	v_mfma_f32_16x16x32_bf16 v[0:3], v[134:137], v[190:193], v[90:93]
	v_mfma_f32_16x16x32_bf16 v[48:51], v[138:141], v[194:197], v[0:3]
	s_barrier
	s_mov_b32 m0, s44
	s_nop 3
	v_lshl_add_u64 v[0:1], v[182:183], 0, s[8:9]
	ds_read_b128 v[68:71], v81
	ds_read_b128 v[86:89], v81 offset:1024
	ds_read_b128 v[90:93], v81 offset:2048
	ds_read_b128 v[220:223], v81 offset:3072
	global_load_lds_dwordx4 v[0:1], off
	v_lshl_add_u64 v[0:1], v[224:225], 0, s[8:9]
	s_mov_b32 m0, s45
	s_nop 0
	global_load_lds_dwordx4 v[0:1], off
	s_barrier
	s_waitcnt lgkmcnt(0)
	s_waitcnt lgkmcnt(0)
	v_mfma_f32_16x16x32_bf16 v[0:3], v[68:71], v[16:19], v[114:117]
	v_mfma_f32_16x16x32_bf16 v[114:117], v[86:89], v[142:145], v[0:3]
	v_mfma_f32_16x16x32_bf16 v[0:3], v[90:93], v[16:19], v[20:23]
	v_mfma_f32_16x16x32_bf16 v[142:145], v[220:223], v[142:145], v[0:3]
	v_mfma_f32_16x16x32_bf16 v[0:3], v[68:71], v[170:173], v[24:27]
	v_mfma_f32_16x16x32_bf16 v[224:227], v[86:89], v[174:177], v[0:3]
	v_mfma_f32_16x16x32_bf16 v[0:3], v[90:93], v[170:173], v[28:31]
	v_mfma_f32_16x16x32_bf16 v[170:173], v[220:223], v[174:177], v[0:3]
	v_mfma_f32_16x16x32_bf16 v[0:3], v[68:71], v[178:181], v[32:35]
	v_mfma_f32_16x16x32_bf16 v[174:177], v[86:89], v[186:189], v[0:3]
	v_mfma_f32_16x16x32_bf16 v[0:3], v[90:93], v[178:181], v[36:39]
	v_mfma_f32_16x16x32_bf16 v[178:181], v[220:223], v[186:189], v[0:3]
	v_mfma_f32_16x16x32_bf16 v[0:3], v[68:71], v[190:193], v[40:43]
	v_mfma_f32_16x16x32_bf16 v[186:189], v[86:89], v[194:197], v[0:3]
	v_mfma_f32_16x16x32_bf16 v[0:3], v[90:93], v[190:193], v[44:47]
	v_mfma_f32_16x16x32_bf16 v[60:63], v[220:223], v[194:197], v[0:3]
	s_mov_b32 m0, s31
	s_nop 4
	v_lshl_add_u64 v[0:1], v[240:241], 0, s[8:9]
	s_barrier
	ds_read_b128 v[24:27], v78 offset:49152
	ds_read_b128 v[28:31], v78 offset:50176
	ds_read_b128 v[40:43], v78 offset:51200
	ds_read_b128 v[190:193], v78 offset:52224
	ds_read_b128 v[194:197], v78 offset:53248
	ds_read_b128 v[228:231], v78 offset:54272
	ds_read_b128 v[232:235], v78 offset:55296
	ds_read_b128 v[236:239], v78 offset:56320
	global_load_lds_dwordx4 v[0:1], off
	v_lshl_add_u64 v[0:1], v[242:243], 0, s[8:9]
	s_mov_b32 m0, s33
	s_nop 0
	global_load_lds_dwordx4 v[0:1], off
	s_barrier
	s_waitcnt lgkmcnt(0)
	s_waitcnt lgkmcnt(0)
	v_mfma_f32_16x16x32_bf16 v[0:3], v[102:105], v[24:27], v[146:149]
	v_mfma_f32_16x16x32_bf16 v[146:149], v[130:133], v[28:31], v[0:3]
	v_mfma_f32_16x16x32_bf16 v[0:3], v[134:137], v[24:27], v[150:153]
	v_mfma_f32_16x16x32_bf16 v[56:59], v[138:141], v[28:31], v[0:3]
	v_mfma_f32_16x16x32_bf16 v[0:3], v[102:105], v[40:43], v[154:157]
	v_mfma_f32_16x16x32_bf16 v[36:39], v[130:133], v[190:193], v[0:3]
	v_mfma_f32_16x16x32_bf16 v[0:3], v[134:137], v[40:43], v[158:161]
	v_mfma_f32_16x16x32_bf16 v[32:35], v[138:141], v[190:193], v[0:3]
	v_mfma_f32_16x16x32_bf16 v[0:3], v[102:105], v[194:197], v[162:165]
	v_mfma_f32_16x16x32_bf16 v[20:23], v[130:133], v[228:231], v[0:3]
	v_mfma_f32_16x16x32_bf16 v[0:3], v[134:137], v[194:197], v[166:169]
	v_mfma_f32_16x16x32_bf16 v[16:19], v[138:141], v[228:231], v[0:3]
	v_mfma_f32_16x16x32_bf16 v[0:3], v[102:105], v[232:235], v[4:7]
	v_mfma_f32_16x16x32_bf16 v[4:7], v[130:133], v[236:239], v[0:3]
	v_mfma_f32_16x16x32_bf16 v[0:3], v[134:137], v[232:235], v[8:11]
	v_mfma_f32_16x16x32_bf16 v[0:3], v[138:141], v[236:239], v[0:3]
	s_barrier
	s_mov_b32 m0, s46
	v_lshl_add_u64 v[8:9], v[244:245], 0, s[8:9]
	global_load_lds_dwordx4 v[8:9], off
	v_lshl_add_u64 v[8:9], v[246:247], 0, s[8:9]
	s_mov_b32 m0, s47
	s_nop 0
	global_load_lds_dwordx4 v[8:9], off
	s_waitcnt vmcnt(6)
	s_barrier
	v_mfma_f32_16x16x32_bf16 v[8:11], v[68:71], v[24:27], v[12:15]
	v_mfma_f32_16x16x32_bf16 v[102:105], v[86:89], v[28:31], v[8:11]
	v_mfma_f32_16x16x32_bf16 v[8:11], v[90:93], v[24:27], v[122:125]
	v_mfma_f32_16x16x32_bf16 v[122:125], v[220:223], v[28:31], v[8:11]
	v_mfma_f32_16x16x32_bf16 v[8:11], v[68:71], v[40:43], v[126:129]
	v_mfma_f32_16x16x32_bf16 v[44:47], v[86:89], v[190:193], v[8:11]
	v_mfma_f32_16x16x32_bf16 v[8:11], v[90:93], v[40:43], v[106:109]
	v_mfma_f32_16x16x32_bf16 v[40:43], v[220:223], v[190:193], v[8:11]
	v_mfma_f32_16x16x32_bf16 v[8:11], v[68:71], v[194:197], v[110:113]
	v_mfma_f32_16x16x32_bf16 v[28:31], v[86:89], v[228:231], v[8:11]
	v_mfma_f32_16x16x32_bf16 v[8:11], v[90:93], v[194:197], v[118:121]
	v_mfma_f32_16x16x32_bf16 v[24:27], v[220:223], v[228:231], v[8:11]
	v_mfma_f32_16x16x32_bf16 v[8:11], v[68:71], v[232:235], v[94:97]
	v_mfma_f32_16x16x32_bf16 v[12:15], v[86:89], v[236:239], v[8:11]
	v_mfma_f32_16x16x32_bf16 v[8:11], v[90:93], v[232:235], v[98:101]
	v_mfma_f32_16x16x32_bf16 v[8:11], v[220:223], v[236:239], v[8:11]
	s_ashr_i32 s20, s20, 8
	s_ashr_i32 s21, s20, 31
	s_lshl_b64 s[20:21], s[20:21], 21
	s_add_u32 s20, s88, s20
	s_addc_u32 s21, s89, s21
	s_lshl_b32 s15, s100, 8
	v_add_u32_e32 v68, s15, v72
	v_ashrrev_i32_e32 v69, 31, v68
	v_lshlrev_b64 v[70:71], 12, v[68:69]
	v_lshl_add_u64 v[90:91], s[20:21], 0, v[70:71]
	v_lshl_or_b32 v70, s101, 8, v76
	v_ashrrev_i32_e32 v71, 31, v70
	v_lshlrev_b64 v[70:71], 2, v[70:71]
	v_pk_mul_f32 v[88:89], v[202:203], 0.5 op_sel_hi:[1,0]
	v_pk_mul_f32 v[86:87], v[200:201], 0.5 op_sel_hi:[1,0]
	v_lshl_add_u64 v[90:91], v[90:91], 0, v[70:71]
	s_barrier
	global_store_dwordx4 v[90:91], v[86:89], off
	v_pk_mul_f32 v[84:85], v[84:85], 0.5 op_sel_hi:[1,0]
	v_pk_mul_f32 v[82:83], v[82:83], 0.5 op_sel_hi:[1,0]
	v_pk_mul_f32 v[88:89], v[206:207], 0.5 op_sel_hi:[1,0]
	v_pk_mul_f32 v[86:87], v[204:205], 0.5 op_sel_hi:[1,0]
	global_store_dwordx4 v[90:91], v[86:89], off offset:64
	v_pk_mul_f32 v[50:51], v[50:51], 0.5 op_sel_hi:[1,0]
	v_pk_mul_f32 v[48:49], v[48:49], 0.5 op_sel_hi:[1,0]
	v_pk_mul_f32 v[88:89], v[116:117], 0.5 op_sel_hi:[1,0]
	v_pk_mul_f32 v[86:87], v[114:115], 0.5 op_sel_hi:[1,0]
	global_store_dwordx4 v[90:91], v[86:89], off offset:512
	v_pk_mul_f32 v[54:55], v[54:55], 0.5 op_sel_hi:[1,0]
	v_pk_mul_f32 v[52:53], v[52:53], 0.5 op_sel_hi:[1,0]
	v_pk_mul_f32 v[88:89], v[144:145], 0.5 op_sel_hi:[1,0]
	v_pk_mul_f32 v[86:87], v[142:143], 0.5 op_sel_hi:[1,0]
	global_store_dwordx4 v[90:91], v[86:89], off offset:576
	v_pk_mul_f32 v[34:35], v[34:35], 0.5 op_sel_hi:[1,0]
	v_pk_mul_f32 v[32:33], v[32:33], 0.5 op_sel_hi:[1,0]
	v_add_u32_e32 v86, s15, v73
	v_ashrrev_i32_e32 v87, 31, v86
	v_lshlrev_b64 v[86:87], 12, v[86:87]
	v_lshl_add_u64 v[90:91], s[20:21], 0, v[86:87]
	v_pk_mul_f32 v[88:89], v[210:211], 0.5 op_sel_hi:[1,0]
	v_pk_mul_f32 v[86:87], v[208:209], 0.5 op_sel_hi:[1,0]
	v_lshl_add_u64 v[90:91], v[90:91], 0, v[70:71]
	global_store_dwordx4 v[90:91], v[86:89], off
	v_pk_mul_f32 v[18:19], v[18:19], 0.5 op_sel_hi:[1,0]
	v_pk_mul_f32 v[16:17], v[16:17], 0.5 op_sel_hi:[1,0]
	v_pk_mul_f32 v[88:89], v[214:215], 0.5 op_sel_hi:[1,0]
	v_pk_mul_f32 v[86:87], v[212:213], 0.5 op_sel_hi:[1,0]
	global_store_dwordx4 v[90:91], v[86:89], off offset:64
	v_pk_mul_f32 v[2:3], v[2:3], 0.5 op_sel_hi:[1,0]
	v_pk_mul_f32 v[0:1], v[0:1], 0.5 op_sel_hi:[1,0]
	v_pk_mul_f32 v[88:89], v[226:227], 0.5 op_sel_hi:[1,0]
	v_pk_mul_f32 v[86:87], v[224:225], 0.5 op_sel_hi:[1,0]
	global_store_dwordx4 v[90:91], v[86:89], off offset:512
	v_pk_mul_f32 v[38:39], v[38:39], 0.5 op_sel_hi:[1,0]
	v_pk_mul_f32 v[36:37], v[36:37], 0.5 op_sel_hi:[1,0]
	v_pk_mul_f32 v[88:89], v[172:173], 0.5 op_sel_hi:[1,0]
	v_pk_mul_f32 v[86:87], v[170:171], 0.5 op_sel_hi:[1,0]
	global_store_dwordx4 v[90:91], v[86:89], off offset:576
	v_pk_mul_f32 v[22:23], v[22:23], 0.5 op_sel_hi:[1,0]
	v_pk_mul_f32 v[20:21], v[20:21], 0.5 op_sel_hi:[1,0]
	v_add_u32_e32 v86, s15, v74
	v_ashrrev_i32_e32 v87, 31, v86
	v_lshlrev_b64 v[86:87], 12, v[86:87]
	v_lshl_add_u64 v[90:91], s[20:21], 0, v[86:87]
	v_lshl_add_u64 v[90:91], v[90:91], 0, v[70:71]
	global_store_dwordx4 v[90:91], v[82:85], off offset:64
	v_pk_mul_f32 v[88:89], v[218:219], 0.5 op_sel_hi:[1,0]
	v_pk_mul_f32 v[86:87], v[216:217], 0.5 op_sel_hi:[1,0]
	v_pk_mul_f32 v[84:85], v[176:177], 0.5 op_sel_hi:[1,0]
	v_pk_mul_f32 v[82:83], v[174:175], 0.5 op_sel_hi:[1,0]
	global_store_dwordx4 v[90:91], v[82:85], off offset:512
	v_pk_mul_f32 v[6:7], v[6:7], 0.5 op_sel_hi:[1,0]
	v_pk_mul_f32 v[4:5], v[4:5], 0.5 op_sel_hi:[1,0]
	v_pk_mul_f32 v[84:85], v[180:181], 0.5 op_sel_hi:[1,0]
	v_pk_mul_f32 v[82:83], v[178:179], 0.5 op_sel_hi:[1,0]
	global_store_dwordx4 v[90:91], v[82:85], off offset:576
	s_add_i32 s36, s36, s37
	s_andn2_b64 vcc, exec, s[16:17]
	v_add_u32_e32 v82, s15, v75
	v_ashrrev_i32_e32 v83, 31, v82
	v_lshlrev_b64 v[82:83], 12, v[82:83]
	v_lshl_add_u64 v[82:83], s[20:21], 0, v[82:83]
	v_lshl_add_u64 v[82:83], v[82:83], 0, v[70:71]
	global_store_dwordx4 v[82:83], v[48:51], off offset:64
	global_store_dwordx4 v[82:83], v[52:55], off
	s_mov_b32 s101, s48
	v_pk_mul_f32 v[50:51], v[188:189], 0.5 op_sel_hi:[1,0]
	v_pk_mul_f32 v[48:49], v[186:187], 0.5 op_sel_hi:[1,0]
	global_store_dwordx4 v[82:83], v[48:51], off offset:512
	s_mov_b32 s100, s49
	s_mov_b64 s[22:23], s[0:1]
	v_pk_mul_f32 v[50:51], v[62:63], 0.5 op_sel_hi:[1,0]
	v_pk_mul_f32 v[48:49], v[60:61], 0.5 op_sel_hi:[1,0]
	global_store_dwordx4 v[82:83], v[48:51], off offset:576
	s_mov_b64 s[24:25], s[18:19]
	global_store_dwordx4 v[90:91], v[86:89], off
	v_add_u32_e32 v48, 0x80, v68
	v_ashrrev_i32_e32 v49, 31, v48
	v_lshlrev_b64 v[48:49], 12, v[48:49]
	v_lshl_add_u64 v[52:53], s[20:21], 0, v[48:49]
	v_pk_mul_f32 v[50:51], v[148:149], 0.5 op_sel_hi:[1,0]
	v_pk_mul_f32 v[48:49], v[146:147], 0.5 op_sel_hi:[1,0]
	v_lshl_add_u64 v[52:53], v[52:53], 0, v[70:71]
	global_store_dwordx4 v[52:53], v[48:51], off
	s_nop 1
	v_pk_mul_f32 v[50:51], v[58:59], 0.5 op_sel_hi:[1,0]
	v_pk_mul_f32 v[48:49], v[56:57], 0.5 op_sel_hi:[1,0]
	global_store_dwordx4 v[52:53], v[48:51], off offset:64
	s_nop 1
	v_pk_mul_f32 v[50:51], v[104:105], 0.5 op_sel_hi:[1,0]
	v_pk_mul_f32 v[48:49], v[102:103], 0.5 op_sel_hi:[1,0]
	global_store_dwordx4 v[52:53], v[48:51], off offset:512
	s_nop 1
	v_pk_mul_f32 v[50:51], v[124:125], 0.5 op_sel_hi:[1,0]
	v_pk_mul_f32 v[48:49], v[122:123], 0.5 op_sel_hi:[1,0]
	global_store_dwordx4 v[52:53], v[48:51], off offset:576
	s_nop 1
	v_add_u32_e32 v48, 0x90, v68
	v_ashrrev_i32_e32 v49, 31, v48
	v_lshlrev_b64 v[48:49], 12, v[48:49]
	v_lshl_add_u64 v[48:49], s[20:21], 0, v[48:49]
	v_lshl_add_u64 v[48:49], v[48:49], 0, v[70:71]
	global_store_dwordx4 v[48:49], v[32:35], off offset:64
	global_store_dwordx4 v[48:49], v[36:39], off
	s_nop 0
	v_pk_mul_f32 v[34:35], v[46:47], 0.5 op_sel_hi:[1,0]
	v_pk_mul_f32 v[32:33], v[44:45], 0.5 op_sel_hi:[1,0]
	global_store_dwordx4 v[48:49], v[32:35], off offset:512
	s_nop 1
	v_pk_mul_f32 v[34:35], v[42:43], 0.5 op_sel_hi:[1,0]
	v_pk_mul_f32 v[32:33], v[40:41], 0.5 op_sel_hi:[1,0]
	global_store_dwordx4 v[48:49], v[32:35], off offset:576
	s_nop 1
	v_add_u32_e32 v32, 0xa0, v68
	v_ashrrev_i32_e32 v33, 31, v32
	v_lshlrev_b64 v[32:33], 12, v[32:33]
	v_lshl_add_u64 v[32:33], s[20:21], 0, v[32:33]
	v_lshl_add_u64 v[32:33], v[32:33], 0, v[70:71]
	global_store_dwordx4 v[32:33], v[16:19], off offset:64
	global_store_dwordx4 v[32:33], v[20:23], off
	s_nop 0
	v_pk_mul_f32 v[18:19], v[30:31], 0.5 op_sel_hi:[1,0]
	v_pk_mul_f32 v[16:17], v[28:29], 0.5 op_sel_hi:[1,0]
	global_store_dwordx4 v[32:33], v[16:19], off offset:512
	s_nop 1
	v_pk_mul_f32 v[18:19], v[26:27], 0.5 op_sel_hi:[1,0]
	v_pk_mul_f32 v[16:17], v[24:25], 0.5 op_sel_hi:[1,0]
	global_store_dwordx4 v[32:33], v[16:19], off offset:576
	s_nop 1
	v_add_u32_e32 v16, 0xb0, v68
	v_ashrrev_i32_e32 v17, 31, v16
	v_lshlrev_b64 v[16:17], 12, v[16:17]
	v_lshl_add_u64 v[16:17], s[20:21], 0, v[16:17]
	v_lshl_add_u64 v[16:17], v[16:17], 0, v[70:71]
	global_store_dwordx4 v[16:17], v[0:3], off offset:64
	s_mov_b32 s20, s14
	global_store_dwordx4 v[16:17], v[4:7], off
	v_pk_mul_f32 v[2:3], v[14:15], 0.5 op_sel_hi:[1,0]
	v_pk_mul_f32 v[0:1], v[12:13], 0.5 op_sel_hi:[1,0]
	global_store_dwordx4 v[16:17], v[0:3], off offset:512
	s_nop 1
	v_pk_mul_f32 v[2:3], v[10:11], 0.5 op_sel_hi:[1,0]
	v_pk_mul_f32 v[0:1], v[8:9], 0.5 op_sel_hi:[1,0]
	global_store_dwordx4 v[16:17], v[0:3], off offset:576
	s_cbranch_vccz .LBB0_1903
.LBB0_1897:
	s_add_i32 s98, s94, s98
	s_cmpk_lt_i32 s98, 0x58
	s_cselect_b64 s[18:19], -1, 0
	s_cmpk_gt_i32 s98, 0x57
	s_cselect_b64 s[16:17], -1, 0
	s_and_b64 vcc, exec, s[16:17]
	s_cbranch_vccnz .LBB0_1899
	s_bfe_u32 s48, s98, 0x20001
	s_and_b32 s49, s98, 1
	s_and_b32 s14, s36, 0xffffff00
